# scan pass 2 spread over all 256 workgroups (4 row-waves each, one per SIMD) instead of 128 workgroups x 8 waves; on top of v14
# speedup vs baseline: 1.0135x; 1.0036x over previous
; __device__ __forceinline__ void scan_pass2(const Ctx&, unsigned char* ws) { const Ctx c = mk_ctx();
;     float* PL = (float*)(ws + WS_R + R_PL); const int lane = c.lane;
;     const int xcd_ = blockIdx.x & 7, tt_ = (blockIdx.x >> 3) * 8 + c.wid;
;     for (int task = (gridDim.x == 256) ? ((tt_ < 128) ? ((xcd_ + 8 * (tt_ >> 6)) * 64 + (tt_ & 63)) : 16 * 64) : c.gw; task < 16 * 64; task += (gridDim.x == 256) ? 16 * 64 : c.NGW) { const int chain = task >> 6, i = task & 63;
.LBB0_2027:
	s_or_b64 exec, exec, s[0:1]
	s_mov_b64 s[0:1], src_shared_base
	v_readlane_b32 s0, v254, 4
	s_cmp_lg_u32 s0, -1
	s_cselect_b32 s0, s0, 0
	s_cselect_b32 s1, s1, 0
	s_waitcnt lgkmcnt(0)
	v_mov_b32_e32 v2, s0
	v_mov_b32_e32 v3, s1
	s_barrier
	ds_read_b64 v[2:3], v2
	s_waitcnt lgkmcnt(0)
	v_mov_b32_e32 v1, v147
	v_readlane_b32 s0, v254, 35
	v_readlane_b32 s1, v254, 36
	v_readlane_b32 s4, v254, 0
	v_readfirstlane_b32 s5, v1
	s_andn2_b64 vcc, exec, s[0:1]
	s_ashr_i32 s5, s5, 6
	s_waitcnt lgkmcnt(0)
	v_readfirstlane_b32 s1, v3
	v_readfirstlane_b32 s0, v2
	s_cbranch_vccnz .LBB0_2029
	v_readlane_b32 s4, v254, 33
	s_lshr_b32 s4, s4, 1
	s_add_i32 s4, s5, s4
	s_cmpk_gt_i32 s5, 3
	s_cselect_b32 s5, 0x80, s4
	s_lshr_b32 s4, s5, 3
	s_and_b32 s4, s4, 0x3fffff8
	v_readlane_b32 s6, v254, 34
	s_or_b32 s4, s4, s6
	s_lshl_b32 s4, s4, 6
	s_and_b32 s6, s5, 63
	s_or_b32 s4, s4, s6
	s_cmpk_lt_i32 s5, 0x80
	s_cselect_b32 s4, s4, 0x400
	s_cmpk_gt_i32 s4, 0x3ff
	s_cbranch_scc0 .LBB0_2030
	s_branch .LBB0_2034
